# phase-33 load balance: workgroups 0-15 (two hyena_filters items) hand their third hyena_dwconv_t round to one extra partial round of the other 240 workgroups
# speedup vs baseline: 1.0027x; 1.0027x over previous
.LBB0_926:
	s_and_b64 vcc, exec, s[0:1]
	s_cbranch_vccz .LBB0_960
	v_mov_b32_e32 v0, v192
	s_mov_b64 s[0:1], 0x60000
	v_ashrrev_i32_e32 v1, 31, v0
	s_waitcnt vmcnt(0)
	v_lshl_add_u64 v[110:111], s[82:83], 0, v[0:1]
	v_cmp_gt_u64_e32 vcc, s[0:1], v[110:111]
	s_and_saveexec_b64 s[6:7], vcc
	s_cbranch_execz .LBB0_934
	s_add_u32 s8, s92, 0xa800000
	s_addc_u32 s9, s93, 0
	s_mov_b64 s[10:11], 0
	v_mov_b32_e32 v214, -1
	v_mov_b32_e32 v215, -1
	s_cmp_eq_u32 s38, 0x20000
	s_cbranch_scc0 .Ldw_nobal
	s_lshr_b32 s0, s82, 9
	s_cmp_lt_u32 s0, 16
	s_cbranch_scc0 .Ldw_others
	v_mov_b32_e32 v215, 0x40000
	s_branch .Ldw_nobal
.Ldw_others:
	s_sub_i32 s0, s0, 16
	v_mov_b32_e32 v214, 0xf0
	v_mad_u32_u24 v214, v192, v214, s0

.LBB0_929:
	s_or_b64 exec, exec, s[0:1]
	s_waitcnt vmcnt(0)
	v_lshlrev_b32_e32 v130, 16, v32
	v_lshlrev_b32_e32 v70, 16, v52
	v_and_b32_e32 v90, 0xffff0000, v52
	v_lshlrev_b32_e32 v108, 16, v53
	v_and_b32_e32 v120, 0xffff0000, v53
	v_mov_b32_e32 v52, v20
	v_mov_b32_e32 v53, v16
	v_mov_b32_e32 v68, v130
	v_lshlrev_b32_e32 v128, 16, v54
	v_and_b32_e32 v136, 0xffff0000, v54
	v_lshlrev_b32_e32 v140, 16, v55
	v_and_b32_e32 v142, 0xffff0000, v55
	v_lshlrev_b32_e32 v71, 16, v102
	v_lshlrev_b32_e32 v55, 16, v44
	v_lshlrev_b32_e32 v54, 16, v40
	v_lshlrev_b32_e32 v131, 16, v36
	v_pk_mul_f32 v[68:69], v[52:53], v[68:69]
	v_lshlrev_b32_e32 v125, 16, v60
	v_pk_fma_f32 v[52:53], v[52:53], v[70:71], v[68:69] op_sel:[0,0,1] op_sel_hi:[1,0,0]
	v_pk_mov_b32 v[68:69], v[130:131], v[54:55] op_sel:[1,0]
	v_pk_fma_f32 v[52:53], v[24:25], v[130:131], v[52:53] op_sel_hi:[0,1,1]
	v_pk_mul_f32 v[68:69], v[20:21], v[68:69] op_sel_hi:[0,1]
	v_pk_fma_f32 v[68:69], v[16:17], v[130:131], v[68:69] op_sel_hi:[0,1,1]
	v_pk_fma_f32 v[68:69], v[24:25], v[54:55], v[68:69] op_sel_hi:[0,1,1]
	v_lshlrev_b32_e32 v124, 16, v48
	v_pk_add_f32 v[52:53], v[28:29], v[52:53] op_sel_hi:[0,1]
	v_pk_add_f32 v[68:69], v[28:29], v[68:69] op_sel_hi:[0,1]
	v_cvt_pk_bf16_f32 v52, v52, v53
	v_cvt_pk_bf16_f32 v53, v68, v69
	v_pk_mov_b32 v[68:69], v[54:55], v[124:125] op_sel:[1,0]
	v_lshlrev_b32_e32 v123, 16, v72
	v_lshlrev_b32_e32 v122, 16, v64
	v_pk_mul_f32 v[68:69], v[20:21], v[68:69] op_sel_hi:[0,1]
	v_pk_fma_f32 v[54:55], v[16:17], v[54:55], v[68:69] op_sel_hi:[0,1,1]
	v_pk_mov_b32 v[68:69], v[124:125], v[122:123] op_sel:[1,0]
	v_pk_fma_f32 v[54:55], v[24:25], v[124:125], v[54:55] op_sel_hi:[0,1,1]
	v_pk_mul_f32 v[68:69], v[20:21], v[68:69] op_sel_hi:[0,1]
	v_pk_fma_f32 v[68:69], v[16:17], v[124:125], v[68:69] op_sel_hi:[0,1,1]
	v_pk_fma_f32 v[68:69], v[24:25], v[122:123], v[68:69] op_sel_hi:[0,1,1]
	v_lshlrev_b32_e32 v115, 16, v80
	v_lshlrev_b32_e32 v114, 16, v76
	v_pk_add_f32 v[54:55], v[28:29], v[54:55] op_sel_hi:[0,1]
	v_pk_add_f32 v[68:69], v[28:29], v[68:69] op_sel_hi:[0,1]
	v_cvt_pk_bf16_f32 v54, v54, v55
	v_cvt_pk_bf16_f32 v55, v68, v69
	v_pk_mov_b32 v[68:69], v[122:123], v[114:115] op_sel:[1,0]
	v_lshlrev_b32_e32 v100, 16, v84
	v_lshlrev_b32_e32 v101, 16, v96
	v_pk_mul_f32 v[68:69], v[20:21], v[68:69] op_sel_hi:[0,1]
	v_pk_fma_f32 v[68:69], v[16:17], v[122:123], v[68:69] op_sel_hi:[0,1,1]
	v_pk_mov_b32 v[122:123], v[114:115], v[100:101] op_sel:[1,0]
	v_and_b32_e32 v164, 0xffff0000, v32
	v_pk_mul_f32 v[122:123], v[20:21], v[122:123] op_sel_hi:[0,1]
	v_mov_b32_e32 v166, v21
	v_mov_b32_e32 v167, v17
	v_mov_b32_e32 v88, v164
	v_pk_fma_f32 v[68:69], v[24:25], v[114:115], v[68:69] op_sel_hi:[0,1,1]
	v_pk_fma_f32 v[114:115], v[16:17], v[114:115], v[122:123] op_sel_hi:[0,1,1]
	v_and_b32_e32 v161, 0xffff0000, v44
	v_and_b32_e32 v160, 0xffff0000, v40
	v_and_b32_e32 v165, 0xffff0000, v36
	v_pk_mul_f32 v[88:89], v[166:167], v[88:89]
	v_pk_fma_f32 v[114:115], v[24:25], v[100:101], v[114:115] op_sel_hi:[0,1,1]
	v_pk_fma_f32 v[88:89], v[166:167], v[90:91], v[88:89] op_sel:[0,0,1] op_sel_hi:[1,0,0]
	v_pk_mov_b32 v[90:91], v[164:165], v[160:161] op_sel:[1,0]
	v_lshlrev_b32_e32 v117, 16, v92
	v_mov_b32_e32 v116, v101
	v_pk_add_f32 v[68:69], v[28:29], v[68:69] op_sel_hi:[0,1]
	v_pk_add_f32 v[114:115], v[28:29], v[114:115] op_sel_hi:[0,1]
	v_pk_mul_f32 v[90:91], v[20:21], v[90:91] op_sel:[1,0]
	v_cvt_pk_bf16_f32 v68, v68, v69
	v_cvt_pk_bf16_f32 v69, v114, v115
	v_pk_mul_f32 v[114:115], v[20:21], v[116:117] op_sel_hi:[0,1]
	v_pk_fma_f32 v[90:91], v[16:17], v[164:165], v[90:91] op_sel:[1,0,0]
	v_mov_b32_e32 v70, v117
	v_pk_fma_f32 v[100:101], v[16:17], v[100:101], v[114:115] op_sel_hi:[0,1,1]
	v_pk_fma_f32 v[88:89], v[24:25], v[164:165], v[88:89] op_sel:[1,0,0]
	v_pk_fma_f32 v[90:91], v[24:25], v[160:161], v[90:91] op_sel:[1,0,0]
	v_pk_fma_f32 v[100:101], v[24:25], v[70:71], v[100:101] op_sel_hi:[0,1,1]
	v_and_b32_e32 v131, 0xffff0000, v60
	v_and_b32_e32 v130, 0xffff0000, v48
	v_pk_add_f32 v[88:89], v[28:29], v[88:89] op_sel:[1,0]
	v_pk_add_f32 v[90:91], v[28:29], v[90:91] op_sel:[1,0]
	v_pk_add_f32 v[100:101], v[28:29], v[100:101] op_sel_hi:[0,1]
	v_cvt_pk_bf16_f32 v88, v88, v89
	v_cvt_pk_bf16_f32 v89, v90, v91
	v_pk_mov_b32 v[90:91], v[160:161], v[130:131] op_sel:[1,0]
	v_cvt_pk_bf16_f32 v70, v100, v101
	v_and_b32_e32 v101, 0xffff0000, v72
	v_and_b32_e32 v100, 0xffff0000, v64
	v_pk_mul_f32 v[90:91], v[20:21], v[90:91] op_sel:[1,0]
	v_and_b32_e32 v123, 0xffff0000, v80
	v_pk_fma_f32 v[90:91], v[16:17], v[160:161], v[90:91] op_sel:[1,0,0]
	v_pk_mov_b32 v[160:161], v[130:131], v[100:101] op_sel:[1,0]
	v_pk_fma_f32 v[90:91], v[24:25], v[130:131], v[90:91] op_sel:[1,0,0]
	v_pk_mul_f32 v[160:161], v[20:21], v[160:161] op_sel:[1,0]
	v_and_b32_e32 v122, 0xffff0000, v76
	v_pk_fma_f32 v[130:131], v[16:17], v[130:131], v[160:161] op_sel:[1,0,0]
	v_pk_add_f32 v[90:91], v[28:29], v[90:91] op_sel:[1,0]
	v_pk_fma_f32 v[130:131], v[24:25], v[100:101], v[130:131] op_sel:[1,0,0]
	v_cvt_pk_bf16_f32 v90, v90, v91
	v_pk_add_f32 v[130:131], v[28:29], v[130:131] op_sel:[1,0]
	v_and_b32_e32 v115, 0xffff0000, v96
	v_cvt_pk_bf16_f32 v91, v130, v131
	v_pk_mov_b32 v[130:131], v[100:101], v[122:123] op_sel:[1,0]
	v_and_b32_e32 v114, 0xffff0000, v84
	v_pk_mul_f32 v[130:131], v[20:21], v[130:131] op_sel:[1,0]
	v_lshlrev_b32_e32 v172, 16, v33
	v_pk_fma_f32 v[100:101], v[16:17], v[100:101], v[130:131] op_sel:[1,0,0]
	v_pk_mov_b32 v[130:131], v[122:123], v[114:115] op_sel:[1,0]
	v_mov_b32_e32 v174, v22
	v_pk_mul_f32 v[130:131], v[20:21], v[130:131] op_sel:[1,0]
	v_mov_b32_e32 v175, v18
	v_mov_b32_e32 v106, v172
	v_and_b32_e32 v36, 0xffff0000, v33
	v_pk_fma_f32 v[100:101], v[24:25], v[122:123], v[100:101] op_sel:[1,0,0]
	v_pk_fma_f32 v[122:123], v[16:17], v[122:123], v[130:131] op_sel:[1,0,0]
	v_lshlrev_b32_e32 v167, 16, v45
	v_lshlrev_b32_e32 v166, 16, v41
	v_lshlrev_b32_e32 v173, 16, v37
	v_pk_mul_f32 v[106:107], v[174:175], v[106:107]
	v_mov_b32_e32 v32, v23
	v_mov_b32_e32 v33, v19
	v_mov_b32_e32 v118, v36
	v_pk_fma_f32 v[122:123], v[24:25], v[114:115], v[122:123] op_sel:[1,0,0]
	v_pk_fma_f32 v[106:107], v[174:175], v[108:109], v[106:107] op_sel:[0,0,1] op_sel_hi:[1,0,0]
	v_pk_mov_b32 v[108:109], v[172:173], v[166:167] op_sel:[1,0]
	v_and_b32_e32 v44, 0xffff0000, v41
	v_pk_mul_f32 v[40:41], v[32:33], v[118:119]
	v_and_b32_e32 v133, 0xffff0000, v92
	v_mov_b32_e32 v132, v115
	v_pk_add_f32 v[100:101], v[28:29], v[100:101] op_sel:[1,0]
	v_pk_add_f32 v[122:123], v[28:29], v[122:123] op_sel:[1,0]
	v_pk_mul_f32 v[108:109], v[22:23], v[108:109] op_sel_hi:[0,1]
	v_and_b32_e32 v37, 0xffff0000, v37
	v_pk_fma_f32 v[32:33], v[32:33], v[120:121], v[40:41] op_sel:[0,0,1] op_sel_hi:[1,0,0]
	v_mov_b32_e32 v40, v27
	v_cvt_pk_bf16_f32 v100, v100, v101
	v_cvt_pk_bf16_f32 v101, v122, v123
	v_pk_mul_f32 v[122:123], v[20:21], v[132:133] op_sel:[1,0]
	v_pk_fma_f32 v[108:109], v[18:19], v[172:173], v[108:109] op_sel_hi:[0,1,1]
	v_and_b32_e32 v45, 0xffff0000, v45
	v_pk_fma_f32 v[32:33], v[40:41], v[36:37], v[32:33] op_sel_hi:[0,1,1]
	v_mov_b32_e32 v48, v31
	v_and_b32_e32 v125, 0xffff0000, v102
	v_mov_b32_e32 v124, v133
	v_pk_fma_f32 v[114:115], v[16:17], v[114:115], v[122:123] op_sel:[1,0,0]
	v_lshlrev_b32_e32 v130, 16, v77
	v_pk_fma_f32 v[106:107], v[26:27], v[172:173], v[106:107] op_sel_hi:[0,1,1]
	v_pk_fma_f32 v[108:109], v[26:27], v[166:167], v[108:109] op_sel_hi:[0,1,1]
	v_and_b32_e32 v80, 0xffff0000, v77
	v_pk_add_f32 v[32:33], v[48:49], v[32:33] op_sel_hi:[0,1]
	v_mov_b32_e32 v64, v23
	v_pk_mov_b32 v[76:77], v[36:37], v[44:45] op_sel:[1,0]
	v_pk_fma_f32 v[114:115], v[24:25], v[124:125], v[114:115] op_sel:[1,0,0]
	v_lshlrev_b32_e32 v165, 16, v61
	v_lshlrev_b32_e32 v164, 16, v49
	v_pk_add_f32 v[106:107], v[30:31], v[106:107] op_sel_hi:[0,1]
	v_pk_add_f32 v[108:109], v[30:31], v[108:109] op_sel_hi:[0,1]
	v_cvt_pk_bf16_f32 v118, v32, v33
	v_mov_b32_e32 v32, v19
	v_pk_mul_f32 v[76:77], v[64:65], v[76:77] op_sel_hi:[0,1]
	v_pk_add_f32 v[114:115], v[28:29], v[114:115] op_sel:[1,0]
	v_cvt_pk_bf16_f32 v106, v106, v107
	v_cvt_pk_bf16_f32 v107, v108, v109
	v_pk_mov_b32 v[108:109], v[166:167], v[164:165] op_sel:[1,0]
	v_pk_fma_f32 v[36:37], v[32:33], v[36:37], v[76:77] op_sel_hi:[0,1,1]
	v_cvt_pk_bf16_f32 v102, v114, v115
	v_lshlrev_b32_e32 v115, 16, v73
	v_lshlrev_b32_e32 v114, 16, v65
	v_pk_mul_f32 v[108:109], v[22:23], v[108:109] op_sel_hi:[0,1]
	v_pk_fma_f32 v[36:37], v[40:41], v[44:45], v[36:37] op_sel_hi:[0,1,1]
	v_pk_fma_f32 v[108:109], v[18:19], v[166:167], v[108:109] op_sel_hi:[0,1,1]
	v_pk_mov_b32 v[166:167], v[164:165], v[114:115] op_sel:[1,0]
	v_and_b32_e32 v61, 0xffff0000, v61
	v_and_b32_e32 v60, 0xffff0000, v49
	v_pk_add_f32 v[36:37], v[48:49], v[36:37] op_sel_hi:[0,1]
	v_pk_mul_f32 v[166:167], v[22:23], v[166:167] op_sel_hi:[0,1]
	v_cvt_pk_bf16_f32 v119, v36, v37
	v_pk_mov_b32 v[36:37], v[44:45], v[60:61] op_sel:[1,0]
	v_pk_fma_f32 v[108:109], v[26:27], v[164:165], v[108:109] op_sel_hi:[0,1,1]
	v_pk_fma_f32 v[164:165], v[18:19], v[164:165], v[166:167] op_sel_hi:[0,1,1]
	v_pk_mul_f32 v[36:37], v[64:65], v[36:37] op_sel_hi:[0,1]
	v_pk_fma_f32 v[164:165], v[26:27], v[114:115], v[164:165] op_sel_hi:[0,1,1]
	v_pk_fma_f32 v[36:37], v[32:33], v[44:45], v[36:37] op_sel_hi:[0,1,1]
	v_lshlrev_b32_e32 v131, 16, v81
	v_pk_add_f32 v[108:109], v[30:31], v[108:109] op_sel_hi:[0,1]
	v_pk_add_f32 v[164:165], v[30:31], v[164:165] op_sel_hi:[0,1]
	v_pk_fma_f32 v[36:37], v[40:41], v[60:61], v[36:37] op_sel_hi:[0,1,1]
	v_cvt_pk_bf16_f32 v108, v108, v109
	v_cvt_pk_bf16_f32 v109, v164, v165
	v_pk_mov_b32 v[164:165], v[114:115], v[130:131] op_sel:[1,0]
	v_and_b32_e32 v73, 0xffff0000, v73
	v_and_b32_e32 v72, 0xffff0000, v65
	v_pk_add_f32 v[36:37], v[48:49], v[36:37] op_sel_hi:[0,1]
	v_lshlrev_b32_e32 v122, 16, v85
	v_lshlrev_b32_e32 v123, 16, v97
	v_pk_mul_f32 v[164:165], v[22:23], v[164:165] op_sel_hi:[0,1]
	v_cvt_pk_bf16_f32 v120, v36, v37
	v_pk_mov_b32 v[36:37], v[60:61], v[72:73] op_sel:[1,0]
	v_pk_fma_f32 v[114:115], v[18:19], v[114:115], v[164:165] op_sel_hi:[0,1,1]
	v_pk_mov_b32 v[164:165], v[130:131], v[122:123] op_sel:[1,0]
	v_pk_mul_f32 v[36:37], v[64:65], v[36:37] op_sel_hi:[0,1]
	v_pk_mul_f32 v[164:165], v[22:23], v[164:165] op_sel_hi:[0,1]
	v_pk_fma_f32 v[36:37], v[32:33], v[60:61], v[36:37] op_sel_hi:[0,1,1]
	v_pk_fma_f32 v[114:115], v[26:27], v[130:131], v[114:115] op_sel_hi:[0,1,1]
	v_pk_fma_f32 v[130:131], v[18:19], v[130:131], v[164:165] op_sel_hi:[0,1,1]
	v_pk_fma_f32 v[36:37], v[40:41], v[72:73], v[36:37] op_sel_hi:[0,1,1]
	v_pk_fma_f32 v[130:131], v[26:27], v[122:123], v[130:131] op_sel_hi:[0,1,1]
	v_and_b32_e32 v81, 0xffff0000, v81
	v_pk_add_f32 v[36:37], v[48:49], v[36:37] op_sel_hi:[0,1]
	v_lshlrev_b32_e32 v171, 16, v93
	v_mov_b32_e32 v170, v123
	v_pk_add_f32 v[114:115], v[30:31], v[114:115] op_sel_hi:[0,1]
	v_pk_add_f32 v[130:131], v[30:31], v[130:131] op_sel_hi:[0,1]
	v_cvt_pk_bf16_f32 v121, v36, v37
	v_pk_mov_b32 v[36:37], v[72:73], v[80:81] op_sel:[1,0]
	v_cvt_pk_bf16_f32 v114, v114, v115
	v_cvt_pk_bf16_f32 v115, v130, v131
	v_pk_mul_f32 v[130:131], v[22:23], v[170:171] op_sel_hi:[0,1]
	v_pk_mul_f32 v[36:37], v[64:65], v[36:37] op_sel_hi:[0,1]
	v_lshlrev_b32_e32 v161, 16, v103
	v_mov_b32_e32 v160, v171
	v_pk_fma_f32 v[122:123], v[18:19], v[122:123], v[130:131] op_sel_hi:[0,1,1]
	v_pk_fma_f32 v[36:37], v[32:33], v[72:73], v[36:37] op_sel_hi:[0,1,1]
	v_pk_fma_f32 v[122:123], v[26:27], v[160:161], v[122:123] op_sel_hi:[0,1,1]
	v_pk_fma_f32 v[36:37], v[40:41], v[80:81], v[36:37] op_sel_hi:[0,1,1]
	v_pk_add_f32 v[122:123], v[30:31], v[122:123] op_sel_hi:[0,1]
	v_and_b32_e32 v97, 0xffff0000, v97
	v_and_b32_e32 v96, 0xffff0000, v85
	v_pk_add_f32 v[36:37], v[48:49], v[36:37] op_sel_hi:[0,1]
	v_cvt_pk_bf16_f32 v116, v122, v123
	v_cvt_pk_bf16_f32 v122, v36, v37
	v_pk_mov_b32 v[36:37], v[80:81], v[96:97] op_sel:[1,0]
	v_lshlrev_b32_e32 v72, 16, v34
	v_pk_mul_f32 v[36:37], v[64:65], v[36:37] op_sel_hi:[0,1]
	v_mov_b32_e32 v76, v4
	v_mov_b32_e32 v77, v0
	v_mov_b32_e32 v126, v72
	v_pk_fma_f32 v[36:37], v[32:33], v[80:81], v[36:37] op_sel_hi:[0,1,1]
	v_pk_mul_f32 v[80:81], v[76:77], v[126:127]
	v_pk_fma_f32 v[36:37], v[40:41], v[96:97], v[36:37] op_sel_hi:[0,1,1]
	v_lshlrev_b32_e32 v73, 16, v38
	v_pk_fma_f32 v[76:77], v[76:77], v[128:129], v[80:81] op_sel:[0,0,1] op_sel_hi:[1,0,0]
	v_and_b32_e32 v93, 0xffff0000, v93
	v_mov_b32_e32 v92, v97
	v_pk_add_f32 v[36:37], v[48:49], v[36:37] op_sel_hi:[0,1]
	v_pk_fma_f32 v[76:77], v[8:9], v[72:73], v[76:77] op_sel_hi:[0,1,1]
	v_cvt_pk_bf16_f32 v123, v36, v37
	v_pk_mul_f32 v[36:37], v[64:65], v[92:93] op_sel_hi:[0,1]
	v_lshlrev_b32_e32 v65, 16, v46
	v_lshlrev_b32_e32 v64, 16, v42
	v_pk_add_f32 v[76:77], v[12:13], v[76:77] op_sel_hi:[0,1]
	v_cvt_pk_bf16_f32 v126, v76, v77
	v_pk_mov_b32 v[76:77], v[72:73], v[64:65] op_sel:[1,0]
	v_lshlrev_b32_e32 v45, 16, v62
	v_pk_mul_f32 v[76:77], v[4:5], v[76:77] op_sel_hi:[0,1]
	v_pk_fma_f32 v[72:73], v[0:1], v[72:73], v[76:77] op_sel_hi:[0,1,1]
	v_pk_fma_f32 v[72:73], v[8:9], v[64:65], v[72:73] op_sel_hi:[0,1,1]
	v_lshlrev_b32_e32 v44, 16, v50
	v_pk_add_f32 v[72:73], v[12:13], v[72:73] op_sel_hi:[0,1]
	v_cvt_pk_bf16_f32 v127, v72, v73
	v_pk_mov_b32 v[72:73], v[64:65], v[44:45] op_sel:[1,0]
	v_and_b32_e32 v85, 0xffff0000, v103
	v_pk_mul_f32 v[72:73], v[4:5], v[72:73] op_sel_hi:[0,1]
	v_pk_fma_f32 v[64:65], v[0:1], v[64:65], v[72:73] op_sel_hi:[0,1,1]
	v_mov_b32_e32 v84, v93
	v_pk_fma_f32 v[32:33], v[32:33], v[96:97], v[36:37] op_sel_hi:[0,1,1]
	v_pk_fma_f32 v[64:65], v[8:9], v[44:45], v[64:65] op_sel_hi:[0,1,1]
	v_pk_fma_f32 v[32:33], v[40:41], v[84:85], v[32:33] op_sel_hi:[0,1,1]
	v_lshlrev_b32_e32 v41, 16, v74
	v_lshlrev_b32_e32 v40, 16, v66
	v_pk_add_f32 v[64:65], v[12:13], v[64:65] op_sel_hi:[0,1]
	v_cvt_pk_bf16_f32 v128, v64, v65
	v_pk_mov_b32 v[64:65], v[44:45], v[40:41] op_sel:[1,0]
	v_lshlrev_b32_e32 v37, 16, v82
	v_pk_mul_f32 v[64:65], v[4:5], v[64:65] op_sel_hi:[0,1]
	v_pk_fma_f32 v[44:45], v[0:1], v[44:45], v[64:65] op_sel_hi:[0,1,1]
	v_pk_fma_f32 v[44:45], v[8:9], v[40:41], v[44:45] op_sel_hi:[0,1,1]
	v_lshlrev_b32_e32 v36, 16, v78
	v_pk_add_f32 v[44:45], v[12:13], v[44:45] op_sel_hi:[0,1]
	v_and_b32_e32 v80, 0xffff0000, v34
	v_cvt_pk_bf16_f32 v129, v44, v45
	v_pk_mov_b32 v[44:45], v[40:41], v[36:37] op_sel:[1,0]
	v_mov_b32_e32 v96, v5
	v_mov_b32_e32 v97, v1
	v_mov_b32_e32 v134, v80
	v_pk_mul_f32 v[44:45], v[4:5], v[44:45] op_sel_hi:[0,1]
	v_pk_mul_f32 v[134:135], v[96:97], v[134:135]
	v_pk_fma_f32 v[40:41], v[0:1], v[40:41], v[44:45] op_sel_hi:[0,1,1]
	v_and_b32_e32 v81, 0xffff0000, v38
	v_pk_fma_f32 v[96:97], v[96:97], v[136:137], v[134:135] op_sel:[0,0,1] op_sel_hi:[1,0,0]
	v_mov_b32_e32 v34, v9
	v_pk_add_f32 v[32:33], v[48:49], v[32:33] op_sel_hi:[0,1]
	v_pk_fma_f32 v[40:41], v[8:9], v[36:37], v[40:41] op_sel_hi:[0,1,1]
	v_pk_fma_f32 v[96:97], v[34:35], v[80:81], v[96:97] op_sel_hi:[0,1,1]
	v_mov_b32_e32 v38, v13
	v_cvt_pk_bf16_f32 v124, v32, v33
	v_lshlrev_b32_e32 v32, 16, v86
	v_lshlrev_b32_e32 v33, 16, v98
	v_pk_add_f32 v[40:41], v[12:13], v[40:41] op_sel_hi:[0,1]
	v_and_b32_e32 v77, 0xffff0000, v46
	v_and_b32_e32 v76, 0xffff0000, v42
	v_pk_add_f32 v[96:97], v[38:39], v[96:97] op_sel_hi:[0,1]
	v_cvt_pk_bf16_f32 v130, v40, v41
	v_pk_mov_b32 v[40:41], v[36:37], v[32:33] op_sel:[1,0]
	v_cvt_pk_bf16_f32 v134, v96, v97
	v_mov_b32_e32 v46, v5
	v_pk_mov_b32 v[96:97], v[80:81], v[76:77] op_sel:[1,0]
	v_pk_mul_f32 v[40:41], v[4:5], v[40:41] op_sel_hi:[0,1]
	v_mov_b32_e32 v42, v1
	v_pk_mul_f32 v[96:97], v[46:47], v[96:97] op_sel_hi:[0,1]
	v_pk_fma_f32 v[36:37], v[0:1], v[36:37], v[40:41] op_sel_hi:[0,1,1]
	v_pk_fma_f32 v[80:81], v[42:43], v[80:81], v[96:97] op_sel_hi:[0,1,1]
	v_pk_fma_f32 v[36:37], v[8:9], v[32:33], v[36:37] op_sel_hi:[0,1,1]
	v_pk_fma_f32 v[80:81], v[34:35], v[76:77], v[80:81] op_sel_hi:[0,1,1]
	v_lshlrev_b32_e32 v61, 16, v94
	v_mov_b32_e32 v60, v33
	v_pk_add_f32 v[36:37], v[12:13], v[36:37] op_sel_hi:[0,1]
	v_and_b32_e32 v45, 0xffff0000, v62
	v_and_b32_e32 v44, 0xffff0000, v50
	v_pk_add_f32 v[80:81], v[38:39], v[80:81] op_sel_hi:[0,1]
	v_cvt_pk_bf16_f32 v131, v36, v37
	v_pk_mul_f32 v[36:37], v[4:5], v[60:61] op_sel_hi:[0,1]
	v_cvt_pk_bf16_f32 v135, v80, v81
	v_pk_mov_b32 v[80:81], v[76:77], v[44:45] op_sel:[1,0]
	v_lshlrev_b32_e32 v49, 16, v104
	v_mov_b32_e32 v48, v61
	v_pk_fma_f32 v[32:33], v[0:1], v[32:33], v[36:37] op_sel_hi:[0,1,1]
	v_pk_mul_f32 v[80:81], v[46:47], v[80:81] op_sel_hi:[0,1]
	v_pk_fma_f32 v[32:33], v[8:9], v[48:49], v[32:33] op_sel_hi:[0,1,1]
	v_pk_fma_f32 v[76:77], v[42:43], v[76:77], v[80:81] op_sel_hi:[0,1,1]
	v_pk_add_f32 v[32:33], v[12:13], v[32:33] op_sel_hi:[0,1]
	v_pk_fma_f32 v[76:77], v[34:35], v[44:45], v[76:77] op_sel_hi:[0,1,1]
	v_cvt_pk_bf16_f32 v132, v32, v33
	v_and_b32_e32 v33, 0xffff0000, v74
	v_and_b32_e32 v32, 0xffff0000, v66
	v_pk_add_f32 v[76:77], v[38:39], v[76:77] op_sel_hi:[0,1]
	v_cvt_pk_bf16_f32 v136, v76, v77
	v_pk_mov_b32 v[76:77], v[44:45], v[32:33] op_sel:[1,0]
	v_and_b32_e32 v41, 0xffff0000, v82
	v_pk_mul_f32 v[76:77], v[46:47], v[76:77] op_sel_hi:[0,1]
	v_pk_fma_f32 v[44:45], v[42:43], v[44:45], v[76:77] op_sel_hi:[0,1,1]
	v_pk_fma_f32 v[44:45], v[34:35], v[32:33], v[44:45] op_sel_hi:[0,1,1]
	v_and_b32_e32 v40, 0xffff0000, v78
	v_pk_add_f32 v[44:45], v[38:39], v[44:45] op_sel_hi:[0,1]
	v_cvt_pk_bf16_f32 v137, v44, v45
	v_pk_mov_b32 v[44:45], v[32:33], v[40:41] op_sel:[1,0]
	v_and_b32_e32 v37, 0xffff0000, v98
	v_and_b32_e32 v36, 0xffff0000, v86
	v_pk_mul_f32 v[44:45], v[46:47], v[44:45] op_sel_hi:[0,1]
	v_pk_fma_f32 v[32:33], v[42:43], v[32:33], v[44:45] op_sel_hi:[0,1,1]
	v_pk_mov_b32 v[44:45], v[40:41], v[36:37] op_sel:[1,0]
	v_lshlrev_b32_e32 v166, 16, v35
	v_pk_mul_f32 v[44:45], v[46:47], v[44:45] op_sel_hi:[0,1]
	v_mov_b32_e32 v172, v6
	v_mov_b32_e32 v173, v2
	v_mov_b32_e32 v138, v166
	v_pk_fma_f32 v[32:33], v[34:35], v[40:41], v[32:33] op_sel_hi:[0,1,1]
	v_pk_fma_f32 v[40:41], v[42:43], v[40:41], v[44:45] op_sel_hi:[0,1,1]
	v_lshlrev_b32_e32 v165, 16, v47
	v_lshlrev_b32_e32 v164, 16, v43
	v_lshlrev_b32_e32 v167, 16, v39
	v_pk_mul_f32 v[138:139], v[172:173], v[138:139]
	v_pk_fma_f32 v[40:41], v[34:35], v[36:37], v[40:41] op_sel_hi:[0,1,1]
	v_pk_fma_f32 v[138:139], v[172:173], v[140:141], v[138:139] op_sel:[0,0,1] op_sel_hi:[1,0,0]
	v_pk_mov_b32 v[140:141], v[166:167], v[164:165] op_sel:[1,0]
	v_and_b32_e32 v73, 0xffff0000, v94
	v_mov_b32_e32 v72, v37
	v_pk_add_f32 v[32:33], v[38:39], v[32:33] op_sel_hi:[0,1]
	v_pk_add_f32 v[40:41], v[38:39], v[40:41] op_sel_hi:[0,1]
	v_pk_mul_f32 v[140:141], v[6:7], v[140:141] op_sel_hi:[0,1]
	v_cvt_pk_bf16_f32 v32, v32, v33
	v_cvt_pk_bf16_f32 v33, v40, v41
	v_pk_mul_f32 v[40:41], v[46:47], v[72:73] op_sel_hi:[0,1]
	v_pk_fma_f32 v[140:141], v[2:3], v[166:167], v[140:141] op_sel_hi:[0,1,1]
	v_and_b32_e32 v65, 0xffff0000, v104
	v_mov_b32_e32 v64, v73
	v_pk_fma_f32 v[36:37], v[42:43], v[36:37], v[40:41] op_sel_hi:[0,1,1]
	v_pk_fma_f32 v[138:139], v[10:11], v[166:167], v[138:139] op_sel_hi:[0,1,1]
	v_pk_fma_f32 v[140:141], v[10:11], v[164:165], v[140:141] op_sel_hi:[0,1,1]
	v_pk_fma_f32 v[36:37], v[34:35], v[64:65], v[36:37] op_sel_hi:[0,1,1]
	v_lshlrev_b32_e32 v97, 16, v63
	v_lshlrev_b32_e32 v96, 16, v51
	v_pk_add_f32 v[138:139], v[14:15], v[138:139] op_sel_hi:[0,1]
	v_pk_add_f32 v[140:141], v[14:15], v[140:141] op_sel_hi:[0,1]
	v_pk_add_f32 v[36:37], v[38:39], v[36:37] op_sel_hi:[0,1]
	v_cvt_pk_bf16_f32 v138, v138, v139
	v_cvt_pk_bf16_f32 v139, v140, v141
	v_pk_mov_b32 v[140:141], v[164:165], v[96:97] op_sel:[1,0]
	v_cvt_pk_bf16_f32 v34, v36, v37
	v_lshlrev_b32_e32 v37, 16, v75
	v_lshlrev_b32_e32 v36, 16, v67
	v_pk_mul_f32 v[140:141], v[6:7], v[140:141] op_sel_hi:[0,1]
	v_pk_fma_f32 v[140:141], v[2:3], v[164:165], v[140:141] op_sel_hi:[0,1,1]
	v_pk_mov_b32 v[164:165], v[96:97], v[36:37] op_sel:[1,0]
	v_pk_fma_f32 v[140:141], v[10:11], v[96:97], v[140:141] op_sel_hi:[0,1,1]
	v_pk_mul_f32 v[164:165], v[6:7], v[164:165] op_sel_hi:[0,1]
	v_pk_fma_f32 v[96:97], v[2:3], v[96:97], v[164:165] op_sel_hi:[0,1,1]
	v_pk_fma_f32 v[96:97], v[10:11], v[36:37], v[96:97] op_sel_hi:[0,1,1]
	v_lshlrev_b32_e32 v45, 16, v83
	v_lshlrev_b32_e32 v44, 16, v79
	v_pk_add_f32 v[140:141], v[14:15], v[140:141] op_sel_hi:[0,1]
	v_pk_add_f32 v[96:97], v[14:15], v[96:97] op_sel_hi:[0,1]
	v_cvt_pk_bf16_f32 v140, v140, v141
	v_cvt_pk_bf16_f32 v141, v96, v97
	v_pk_mov_b32 v[96:97], v[36:37], v[44:45] op_sel:[1,0]
	v_lshlrev_b32_e32 v40, 16, v87
	v_lshlrev_b32_e32 v41, 16, v99
	v_pk_mul_f32 v[96:97], v[6:7], v[96:97] op_sel_hi:[0,1]
	v_pk_fma_f32 v[36:37], v[2:3], v[36:37], v[96:97] op_sel_hi:[0,1,1]
	v_pk_mov_b32 v[96:97], v[44:45], v[40:41] op_sel:[1,0]
	v_pk_fma_f32 v[36:37], v[10:11], v[44:45], v[36:37] op_sel_hi:[0,1,1]
	v_pk_mul_f32 v[96:97], v[6:7], v[96:97] op_sel_hi:[0,1]
	v_pk_fma_f32 v[44:45], v[2:3], v[44:45], v[96:97] op_sel_hi:[0,1,1]
	v_pk_fma_f32 v[44:45], v[10:11], v[40:41], v[44:45] op_sel_hi:[0,1,1]
	v_lshlrev_b32_e32 v81, 16, v95
	v_mov_b32_e32 v80, v41
	v_pk_add_f32 v[36:37], v[14:15], v[36:37] op_sel_hi:[0,1]
	v_pk_add_f32 v[44:45], v[14:15], v[44:45] op_sel_hi:[0,1]
	v_cvt_pk_bf16_f32 v36, v36, v37
	v_cvt_pk_bf16_f32 v37, v44, v45
	v_pk_mul_f32 v[44:45], v[6:7], v[80:81] op_sel_hi:[0,1]
	v_lshlrev_b32_e32 v77, 16, v105
	v_mov_b32_e32 v76, v81
	v_pk_fma_f32 v[40:41], v[2:3], v[40:41], v[44:45] op_sel_hi:[0,1,1]
	v_pk_fma_f32 v[40:41], v[10:11], v[76:77], v[40:41] op_sel_hi:[0,1,1]
	v_pk_add_f32 v[40:41], v[14:15], v[40:41] op_sel_hi:[0,1]
	v_and_b32_e32 v42, 0xffff0000, v35
	v_cvt_pk_bf16_f32 v38, v40, v41
	v_and_b32_e32 v47, 0xffff0000, v47
	v_and_b32_e32 v46, 0xffff0000, v43
	v_and_b32_e32 v43, 0xffff0000, v39
	v_mov_b32_e32 v40, v7
	v_mov_b32_e32 v41, v3
	v_mov_b32_e32 v144, v42
	v_and_b32_e32 v44, 0xffff0000, v67
	v_and_b32_e32 v62, 0xffff0000, v51
	v_pk_mul_f32 v[50:51], v[40:41], v[144:145]
	v_mov_b32_e32 v64, v7
	v_pk_mov_b32 v[66:67], v[42:43], v[46:47] op_sel:[1,0]
	v_pk_fma_f32 v[40:41], v[40:41], v[142:143], v[50:51] op_sel:[0,0,1] op_sel_hi:[1,0,0]
	v_mov_b32_e32 v48, v11
	v_mov_b32_e32 v60, v3
	v_pk_mul_f32 v[66:67], v[64:65], v[66:67] op_sel_hi:[0,1]
	v_pk_fma_f32 v[40:41], v[48:49], v[42:43], v[40:41] op_sel_hi:[0,1,1]
	v_pk_fma_f32 v[42:43], v[60:61], v[42:43], v[66:67] op_sel_hi:[0,1,1]
	v_mov_b32_e32 v50, v15
	v_pk_fma_f32 v[42:43], v[48:49], v[46:47], v[42:43] op_sel_hi:[0,1,1]
	v_and_b32_e32 v63, 0xffff0000, v63
	v_pk_add_f32 v[40:41], v[50:51], v[40:41] op_sel_hi:[0,1]
	v_pk_add_f32 v[42:43], v[50:51], v[42:43] op_sel_hi:[0,1]
	v_cvt_pk_bf16_f32 v40, v40, v41
	v_cvt_pk_bf16_f32 v41, v42, v43
	v_pk_mov_b32 v[42:43], v[46:47], v[62:63] op_sel:[1,0]
	v_and_b32_e32 v45, 0xffff0000, v75
	v_pk_mul_f32 v[42:43], v[64:65], v[42:43] op_sel_hi:[0,1]
	v_pk_fma_f32 v[42:43], v[60:61], v[46:47], v[42:43] op_sel_hi:[0,1,1]
	v_pk_mov_b32 v[46:47], v[62:63], v[44:45] op_sel:[1,0]
	v_pk_fma_f32 v[42:43], v[48:49], v[62:63], v[42:43] op_sel_hi:[0,1,1]
	v_pk_mul_f32 v[46:47], v[64:65], v[46:47] op_sel_hi:[0,1]
	v_pk_fma_f32 v[46:47], v[60:61], v[62:63], v[46:47] op_sel_hi:[0,1,1]
	v_pk_fma_f32 v[46:47], v[48:49], v[44:45], v[46:47] op_sel_hi:[0,1,1]
	v_and_b32_e32 v83, 0xffff0000, v83
	v_and_b32_e32 v82, 0xffff0000, v79
	v_pk_add_f32 v[42:43], v[50:51], v[42:43] op_sel_hi:[0,1]
	v_pk_add_f32 v[46:47], v[50:51], v[46:47] op_sel_hi:[0,1]
	v_cvt_pk_bf16_f32 v42, v42, v43
	v_cvt_pk_bf16_f32 v43, v46, v47
	v_pk_mov_b32 v[46:47], v[44:45], v[82:83] op_sel:[1,0]
	v_and_b32_e32 v97, 0xffff0000, v99
	v_and_b32_e32 v96, 0xffff0000, v87
	v_pk_mul_f32 v[46:47], v[64:65], v[46:47] op_sel_hi:[0,1]
	v_pk_fma_f32 v[44:45], v[60:61], v[44:45], v[46:47] op_sel_hi:[0,1,1]
	v_pk_mov_b32 v[46:47], v[82:83], v[96:97] op_sel:[1,0]
	v_pk_fma_f32 v[44:45], v[48:49], v[82:83], v[44:45] op_sel_hi:[0,1,1]
	v_pk_mul_f32 v[46:47], v[64:65], v[46:47] op_sel_hi:[0,1]
	v_pk_fma_f32 v[46:47], v[60:61], v[82:83], v[46:47] op_sel_hi:[0,1,1]
	v_pk_fma_f32 v[46:47], v[48:49], v[96:97], v[46:47] op_sel_hi:[0,1,1]
	v_and_b32_e32 v87, 0xffff0000, v95
	v_mov_b32_e32 v86, v97
	v_pk_add_f32 v[44:45], v[50:51], v[44:45] op_sel_hi:[0,1]
	v_pk_add_f32 v[46:47], v[50:51], v[46:47] op_sel_hi:[0,1]
	v_cvt_pk_bf16_f32 v44, v44, v45
	v_cvt_pk_bf16_f32 v45, v46, v47
	v_pk_mul_f32 v[46:47], v[64:65], v[86:87] op_sel_hi:[0,1]
	v_and_b32_e32 v95, 0xffff0000, v105
	v_mov_b32_e32 v94, v87
	v_pk_fma_f32 v[46:47], v[60:61], v[96:97], v[46:47] op_sel_hi:[0,1,1]
	v_pk_fma_f32 v[46:47], v[48:49], v[94:95], v[46:47] op_sel_hi:[0,1,1]
	v_pk_add_f32 v[46:47], v[50:51], v[46:47] op_sel_hi:[0,1]
	v_mul_f32_e32 v50, v20, v71
	v_and_b32_e32 v35, 0xffff0000, v56
	v_lshlrev_b32_e32 v56, 16, v56
	v_fmac_f32_e32 v50, v16, v117
	v_fmac_f32_e32 v50, v24, v56
	v_add_f32_e32 v60, v28, v50
	v_mul_f32_e32 v50, v21, v125
	v_fmac_f32_e32 v50, v17, v133
	v_fmac_f32_e32 v50, v25, v35
	v_add_f32_e32 v62, v29, v50
	v_mul_f32_e32 v50, v22, v161
	v_lshlrev_b32_e32 v39, 16, v57
	v_fmac_f32_e32 v50, v18, v171
	v_fmac_f32_e32 v50, v26, v39
	v_add_f32_e32 v63, v30, v50
	v_mul_f32_e32 v50, v23, v85
	v_cvt_pk_bf16_f32 v46, v46, v47
	v_and_b32_e32 v47, 0xffff0000, v57
	v_fmac_f32_e32 v50, v19, v93
	v_fmac_f32_e32 v50, v27, v47
	v_add_f32_e32 v64, v31, v50
	v_mul_f32_e32 v50, v4, v49
	v_lshlrev_b32_e32 v48, 16, v58
	v_fmac_f32_e32 v50, v0, v61
	v_fmac_f32_e32 v50, v8, v48
	v_add_f32_e32 v61, v12, v50
	v_mul_f32_e32 v50, v5, v65
	v_and_b32_e32 v57, 0xffff0000, v58
	v_fmac_f32_e32 v50, v1, v73
	v_fmac_f32_e32 v50, v9, v57
	v_add_f32_e32 v66, v13, v50
	v_mul_f32_e32 v50, v6, v77
	v_lshlrev_b32_e32 v58, 16, v59
	v_fmac_f32_e32 v50, v2, v81
	v_fmac_f32_e32 v50, v10, v58
	v_add_f32_e32 v67, v14, v50
	v_mul_f32_e32 v50, v7, v95
	v_and_b32_e32 v59, 0xffff0000, v59
	v_fmac_f32_e32 v50, v3, v87
	v_fmac_f32_e32 v50, v11, v59
	v_add_f32_e32 v72, v15, v50
	v_mov_b32_e32 v50, v16
	v_mov_b32_e32 v51, v24
	v_mov_b32_e32 v142, v71
	v_pk_mul_f32 v[50:51], v[50:51], v[142:143]
	v_mov_b32_e32 v24, v17
	v_fma_f32 v16, v20, v56, v50
	v_add_f32_e32 v16, v16, v51
	v_add_f32_e32 v16, v28, v16
	v_mov_b32_e32 v158, v125
	v_cvt_pk_bf16_f32 v71, v60, v16
	v_pk_mul_f32 v[16:17], v[24:25], v[158:159]
	v_mov_b32_e32 v156, v161
	v_fma_f32 v16, v21, v35, v16
	v_add_f32_e32 v16, v16, v17
	v_add_f32_e32 v16, v29, v16
	v_cvt_pk_bf16_f32 v103, v62, v16
	v_mov_b32_e32 v16, v18
	v_mov_b32_e32 v17, v26
	v_pk_mul_f32 v[16:17], v[16:17], v[156:157]
	v_mov_b32_e32 v26, v19
	v_fma_f32 v16, v22, v39, v16
	v_add_f32_e32 v16, v16, v17
	v_add_f32_e32 v16, v30, v16
	v_mov_b32_e32 v154, v85
	v_cvt_pk_bf16_f32 v117, v63, v16
	v_pk_mul_f32 v[16:17], v[26:27], v[154:155]
	v_mov_b32_e32 v152, v49
	v_fma_f32 v16, v23, v47, v16
	v_add_f32_e32 v16, v16, v17
	v_add_f32_e32 v16, v31, v16
	v_cvt_pk_bf16_f32 v125, v64, v16
	v_mov_b32_e32 v16, v0
	v_mov_b32_e32 v17, v8
	v_pk_mul_f32 v[16:17], v[16:17], v[152:153]
	v_mov_b32_e32 v8, v1
	v_fma_f32 v0, v4, v48, v16
	v_add_f32_e32 v0, v0, v17
	v_add_f32_e32 v0, v12, v0
	v_mov_b32_e32 v150, v65
	v_cvt_pk_bf16_f32 v133, v61, v0
	v_pk_mul_f32 v[0:1], v[8:9], v[150:151]
	v_mov_b32_e32 v148, v77
	v_fma_f32 v0, v5, v57, v0
	v_add_f32_e32 v0, v0, v1
	v_add_f32_e32 v0, v13, v0
	v_cvt_pk_bf16_f32 v35, v66, v0
	v_mov_b32_e32 v0, v2
	v_mov_b32_e32 v1, v10
	v_pk_mul_f32 v[0:1], v[0:1], v[148:149]
	v_mov_b32_e32 v10, v3
	v_fma_f32 v0, v6, v58, v0
	v_add_f32_e32 v0, v0, v1
	v_add_f32_e32 v0, v14, v0
	v_mov_b32_e32 v146, v95
	v_cvt_pk_bf16_f32 v39, v67, v0
	v_pk_mul_f32 v[0:1], v[10:11], v[146:147]
	v_lshlrev_b32_e32 v2, 18, v113
	v_fma_f32 v0, v7, v59, v0
	v_add_f32_e32 v0, v0, v1
	v_add_f32_e32 v0, v15, v0
	v_cvt_pk_bf16_f32 v47, v72, v0
	v_lshlrev_b32_e32 v0, 1, v162
	v_mov_b32_e32 v1, v112
	v_lshl_add_u64 v[0:1], s[8:9], 0, v[0:1]
	v_mov_b32_e32 v3, v112
	v_lshl_add_u64 v[0:1], v[0:1], 0, v[2:3]
	s_mov_b32 s0, 0x8000
	v_add_co_u32_e32 v2, vcc, s0, v0
	s_mov_b32 s0, 0x10000
	s_nop 0
	v_addc_co_u32_e32 v3, vcc, 0, v1, vcc
	global_store_dwordx4 v[0:1], v[52:55], off
	global_store_dwordx4 v[0:1], v[68:71], off offset:16
	global_store_dwordx4 v[2:3], v[88:91], off
	global_store_dwordx4 v[2:3], v[100:103], off offset:16
	v_add_co_u32_e32 v2, vcc, s0, v0
	s_mov_b32 s0, 0x20000
	s_nop 0
	v_addc_co_u32_e32 v3, vcc, 0, v1, vcc
	global_store_dwordx4 v[2:3], v[106:109], off
	global_store_dwordx4 v[2:3], v[114:117], off offset:16
	v_add_co_u32_e32 v2, vcc, s76, v0
	v_lshl_add_u64 v[110:111], v[110:111], 0, s[38:39]
	s_nop 0
	v_addc_co_u32_e32 v3, vcc, 0, v1, vcc
	global_store_dwordx4 v[2:3], v[118:121], off
	global_store_dwordx4 v[2:3], v[122:125], off offset:16
	v_add_co_u32_e32 v2, vcc, s0, v0
	s_mov_b32 s0, 0x28000
	s_nop 0
	v_addc_co_u32_e32 v3, vcc, 0, v1, vcc
	global_store_dwordx4 v[2:3], v[126:129], off
	global_store_dwordx4 v[2:3], v[130:133], off offset:16
	v_add_co_u32_e32 v2, vcc, s0, v0
	s_mov_b32 s0, 0x30000
	s_nop 0
	v_addc_co_u32_e32 v3, vcc, 0, v1, vcc
	global_store_dwordx4 v[2:3], v[134:137], off
	global_store_dwordx4 v[2:3], v[32:35], off offset:16
	v_add_co_u32_e32 v2, vcc, s0, v0
	s_mov_b64 s[0:1], 0x5ffff
	s_nop 0
	v_addc_co_u32_e32 v3, vcc, 0, v1, vcc
	v_add_co_u32_e32 v0, vcc, 0x38000, v0
	global_store_dwordx4 v[2:3], v[138:141], off
	global_store_dwordx4 v[2:3], v[36:39], off offset:16
	v_addc_co_u32_e32 v1, vcc, 0, v1, vcc
	v_cmp_le_u32_e32 vcc, v215, v110
	v_mov_b32_e32 v216, 0x7fffffff
	s_nop 0
	v_cndmask_b32_e32 v110, v110, v216, vcc
	v_cmp_le_u32_e32 vcc, 0x62000, v110
	s_nop 1
	v_cndmask_b32_e64 v216, 0, 1, vcc
	v_cmp_gt_u32_e32 vcc, 0x2000, v214
	s_nop 1
	v_cndmask_b32_e64 v217, 0, 1, vcc
	v_and_b32_e32 v216, v216, v217
	v_cmp_ne_u32_e32 vcc, 0, v216
	v_add_u32_e32 v217, 0x40000, v214
	s_nop 0
	v_cndmask_b32_e32 v110, v110, v217, vcc
	v_cmp_lt_u64_e32 vcc, s[0:1], v[110:111]
	s_or_b64 s[10:11], vcc, s[10:11]
	global_store_dwordx4 v[0:1], v[40:43], off
	global_store_dwordx4 v[0:1], v[44:47], off offset:16
	s_andn2_b64 exec, exec, s[10:11]
	s_cbranch_execz .LBB0_934
